# strategy 4: static s_setprio 1 for the second co-resident workgroup during the out-proj GEMM phase
# speedup vs baseline: 1.0036x; 1.0036x over previous
.LBB0_70:
.LBB0_71:
	v_readlane_b32 s0, v253, 43
	v_readlane_b32 s1, v253, 44
	s_andn2_b64 vcc, exec, s[0:1]
	s_cbranch_vccnz .LBB0_90
	v_mov_b32_e32 v0, v151
	s_ashr_i32 s81, s80, 31
	s_lshl_b64 s[0:1], s[80:81], 21
	v_readlane_b32 s5, v253, 28
	s_add_u32 s5, s5, s0
	v_readlane_b32 s6, v253, 29
	v_readlane_b32 s9, v254, 7
	s_addc_u32 s6, s6, s1
	s_mov_b32 s7, s9
	s_cmp_lt_u32 s9, 32
	s_cbranch_scc1 .Lop_prio_skip
	s_setprio 1
.Lop_prio_skip:
	v_readlane_b32 s8, v255, 34
	s_branch .LBB0_74

.LBB0_90:
	s_mov_b64 s[0:1], 0
	s_setprio 0
